# F1: FFN conv halo fix-up loop: neighbour gate + tap weights loaded with the item's own vectors under the merged mask (one memory round trip per item instead of two); code after it padded to the P16 by
# speedup vs baseline: 1.0034x; 1.0034x over previous
; __device__ __forceinline__ unsigned cvt_pk_bf16(float lo, float hi) { f32x2_t v = {lo, hi}; bf16x2_t b = __builtin_convertvector(v, bf16x2_t); return __builtin_bit_cast(unsigned, b); }
; __device__ __forceinline__ float silu_f(float x) { return x * __builtin_amdgcn_rcpf(1.0f + __builtin_amdgcn_exp2f(-x * LOG2E)); }
; __device__ __forceinline__ void ffn_fixup(const Args& a, int layer, int nrows, int gt, int NT) {
;     ...
;     for (int idx = gt; idx < nblk * 2 * (DFF / 4); idx += NT) {
;         const int c4 = idx % (DFF / 4), bw = idx / (DFF / 4), blk = bw >> 1, which = bw & 1, col = 4 * c4;
;         const int row = blk * 64 + (which ? 63 : 0);
;         const int sb = row < MX ? (blk & 31) : ((blk - MX / 64) & 3), nsb = row < MX ? 32 : 4;
;         const _Float16* sp = SIDE + ((size_t)(blk * 2 + which) * 3) * DFF + col;
;         f32x4 cv = __builtin_convertvector(*(const sh4*)sp, f32x4); const f32x4 vv = __builtin_convertvector(*(const sh4*)(sp + 2 * DFF), f32x4);
;         if (which == 0 && sb > 0) { const f32x4 gl = __builtin_convertvector(*(const sh4*)(SIDE + ((size_t)((blk - 1) * 2 + 1) * 3 + 1) * DFF + col), f32x4); cv += *(const f32x4*)(cw + col) * gl; }
;         if (which == 1 && sb < nsb - 1) { const f32x4 gf = __builtin_convertvector(*(const sh4*)(SIDE + ((size_t)((blk + 1) * 2 + 0) * 3 + 1) * DFF + col), f32x4); cv += *(const f32x4*)(cw + 2 * DFF + col) * gf; }
;         const f32x4 vs = vv * (-LOG2E);
;         u32x2 w; w.x = cvt_pk_bf16(silu_f(cv[0]) * vs[0], silu_f(cv[1]) * vs[1]); w.y = cvt_pk_bf16(silu_f(cv[2]) * vs[2], silu_f(cv[3]) * vs[3]);
;         *(u32x2*)(ACT + (size_t)row * DFF + col) = w;
;     }
.LBB0_110:
	s_mov_b32 s12, 0x2e8ba2e9
	v_mul_hi_i32 v0, v8, s12
	v_lshrrev_b32_e32 v1, 31, v0
	v_ashrrev_i32_e32 v0, 7, v0
	v_add_u32_e32 v11, v0, v1
	v_mul_i32_i24_e32 v0, 0x2c0, v11
	v_lshlrev_b32_e32 v0, 2, v0
	v_sub_u32_e32 v0, v9, v0
	v_mul_i32_i24_e32 v14, 3, v11
	v_mov_b64_e32 v[2:3], s[54:55]
	v_mad_i64_i32 v[2:3], s[12:13], v14, s20, v[2:3]
	v_ashrrev_i32_e32 v1, 31, v0
	v_lshl_add_u64 v[2:3], v[0:1], 1, v[2:3]
	global_load_dwordx2 v[16:17], v[2:3], off
	v_add_co_u32_e32 v2, vcc, 0x2000, v2
	v_ashrrev_i32_e32 v15, 1, v11
	s_nop 0
	v_addc_co_u32_e32 v3, vcc, 0, v3, vcc
	global_load_dwordx2 v[6:7], v[2:3], off offset:3072
	v_bfe_i32 v2, v11, 0, 1
	v_lshlrev_b32_e32 v3, 6, v15
	v_and_or_b32 v10, v2, 63, v3
	s_movk_i32 s12, 0x4000
	v_cmp_gt_i32_e64 s[34:35], s12, v10
	v_and_b32_e32 v12, 1, v11
	v_cmp_eq_u32_e32 vcc, 0, v12
	v_cndmask_b32_e64 v13, 3, 31, s[34:35]
	v_and_b32_e32 v15, v13, v15
	v_cmp_ne_u32_e64 s[34:35], 0, v15
	s_movk_i32 s17, 0x1600
	s_and_b64 s[20:21], vcc, s[34:35]
	v_cmp_ne_u32_e64 s[34:35], v15, v13
	s_andn2_b64 s[34:35], s[34:35], vcc
	s_or_b64 s[20:21], s[20:21], s[34:35]
	v_and_b32_e32 v18, 0xfffffe, v11
	v_mad_i32_i24 v18, v18, 3, 7
	v_add_u32_e32 v19, -2, v14
	v_cndmask_b32_e32 v18, v18, v19, vcc
	v_mov_b32_e32 v22, s36
	v_mov_b32_e32 v23, s37
	v_mov_b32_e32 v24, s8
	v_mov_b32_e32 v25, s9
	v_cndmask_b32_e32 v22, v22, v24, vcc
	v_cndmask_b32_e32 v23, v23, v25, vcc
	s_mov_b64 s[12:13], exec
	s_and_b64 exec, exec, s[20:21]
	s_cbranch_execz .Lfx_nold
	v_mov_b64_e32 v[20:21], s[54:55]
	v_mad_i64_i32 v[20:21], vcc, v18, s17, v[20:21]
	v_lshl_add_u64 v[20:21], v[0:1], 1, v[20:21]
	v_lshl_add_u64 v[22:23], v[0:1], 2, v[22:23]
	global_load_dwordx2 v[20:21], v[20:21], off
	global_load_dwordx4 v[22:25], v[22:23], off
.Lfx_nold:
	s_mov_b64 exec, s[12:13]
	s_waitcnt vmcnt(0)
	v_cvt_f32_f16_e32 v4, v16
	v_cvt_f32_f16_e32 v2, v17
	v_cvt_f32_f16_sdwa v3, v17 dst_sel:DWORD dst_unused:UNUSED_PAD src0_sel:WORD_1
	v_cvt_f32_f16_sdwa v5, v16 dst_sel:DWORD dst_unused:UNUSED_PAD src0_sel:WORD_1
	s_and_b64 exec, exec, s[20:21]
	s_cbranch_execz .Lfx_nofma
	v_cvt_f32_f16_e32 v26, v20
	v_cvt_f32_f16_sdwa v27, v20 dst_sel:DWORD dst_unused:UNUSED_PAD src0_sel:WORD_1
	v_cvt_f32_f16_e32 v28, v21
	v_cvt_f32_f16_sdwa v29, v21 dst_sel:DWORD dst_unused:UNUSED_PAD src0_sel:WORD_1
	s_nop 0
	v_pk_fma_f32 v[4:5], v[22:23], v[26:27], v[4:5]
	v_pk_fma_f32 v[2:3], v[24:25], v[28:29], v[2:3]
.Lfx_nofma:
	s_mov_b64 exec, s[12:13]
	s_branch .LBB0_109
	s_nop 0
	s_nop 0
	s_nop 0
	s_nop 0
	s_nop 0
	s_nop 0
	s_nop 0
	s_nop 0
	s_nop 0
	s_nop 0
	s_nop 0
	s_nop 0
	s_nop 0
	s_nop 0
	s_nop 0
